# odd XCDs start their layer chain ~24 us after the even ones (s_sleep once, after the first barrier) so that the bandwidth-bound phases of the two halves do not collide
# baseline (speedup 1.0000x reference)
; __global__ void __launch_bounds__(NTHREADS, 2) mega(Params p_, int ph_lo, int ph_hi) {
;     ...
;     for (int ph = ph_lo; ph < ph_hi; ++ph) {
;         if (ph == 0) { prologue_phase(p, smem); if (DBL & 32) prologue_phase(p, smem); }
;         else {
;             const int l = (ph - 1) >> 2, s = (ph - 1) & 3;
;             if (s == 0) { norm_phase(p, l); if (DBL & 1) norm_phase(p, l); }
.LBB0_137:
	s_andn2_b64 vcc, exec, s[4:5]
	s_cbranch_vccnz .LBB0_292
	s_cmp_eq_u32 s98, 1
	s_mov_b64 s[4:5], -1
	s_cbranch_scc1 .LBB0_183
	s_cmp_lg_u32 s60, 0
	s_cbranch_scc1 .Lstg_skip
	v_readlane_b32 s4, v254, 0
	s_nop 0
	s_bitcmp1_b32 s4, 0
	s_cbranch_scc0 .Lstg_skip
	s_sleep 127
	s_sleep 127
	s_sleep 127
	s_sleep 127
	s_sleep 127
	s_sleep 127
.Lstg_skip:
	v_mov_b32_e32 v16, v200
	v_readlane_b32 s4, v254, 21
	v_readlane_b32 s100, v254, 22
	s_mov_b32 s101, 0x47ff
	s_cmp_lg_u32 s100, 0x800
	s_cbranch_scc1 .Lnorm_nomap
	s_lshr_b32 s100, s4, 5
	s_lshl_b32 s100, s100, 2
	s_bfe_u32 s4, s4, 0x30002
	s_mulk_i32 s4, 0x900
	s_add_i32 s101, s4, 0x8ff
	s_add_i32 s4, s4, s100
	s_movk_i32 s100, 0x100
